# static priority raise for waves 4-7 also in the two sgu phases (on top of the attention raise)
# baseline (speedup 1.0000x reference)
; #define LAS __attribute__((address_space(3)))
; __device__ __forceinline__ void sgu_phase(const Params& p, LAS unsigned char* lds, int li, int tid, int G, bf16_t* dst) {
;     asm volatile("" : "+v"(tid));
;     unsigned char* ws = p.ws;
;     const int w = tid >> 6, l = tid & 63, lq = l & 15, g4 = l >> 4;
;     const bf16_t* ZVT = (const bf16_t*)(ws + OFF_ZVT2); bf16_t* Z0 = (bf16_t*)(ws + OFF_Z0);
;     const float* vss = (const float*)(ws + OFF_VSS);
;     LAS float* RI = (LAS float*)(lds + 34816);
;     const int c = tid >> 2, q0 = (tid & 3) * 32;
;     u32x4 raw[4]; f32x4 vs = {1.f, 1.f, 1.f, 1.f};
;     int item = blockIdx.x;
;     if (item < 2048) {
;         const int tb = item >> 3, g = item & 7, t0 = tb * 128;
; #pragma unroll
;         for (int i = 0; i < 4; ++i) raw[i] = *(const u32x4*)(ZVT + (size_t)(g * 128 + c) * T + t0 + q0 + 8 * i);
;         if (tid < 128) vs = *(const f32x4*)(vss + (size_t)(t0 + tid) * 32 + g * 4);
;     }
;     for (; item < 2048; item += G) {
;         const int tb = item >> 3, g = item & 7, t0 = tb * 128;
;         __syncthreads();
;         if (tid < 128) RI[tid] = rsqrtf(((vs[0] + vs[1]) + (vs[2] + vs[3])) * (1.f / 128.f) + EPS);
;         const size_t tok = (size_t)(t0 + 16 * w + lq);
;         const bf16_t* WS = (const bf16_t*)(ws + OFF_WSB) + (size_t)(li * 8 + g) * 128 * 128;
.LBB0_823:
	s_or_b64 exec, exec, s[56:57]
	v_bfi_b32 v65, -16, v63, v62
	v_lshlrev_b32_e32 v22, 7, v65
	v_bfe_u32 v24, v62, 4, 2
	v_ashrrev_i32_e32 v23, 31, v22
	v_lshl_add_u64 v[22:23], v[22:23], 1, s[10:11]
	v_lshlrev_b32_e32 v36, 4, v24
	v_lshl_add_u64 v[22:23], v[22:23], 0, v[36:37]
	s_mov_b64 s[0:1], 0x90000
	v_lshl_add_u64 v[40:41], v[22:23], 0, s[0:1]
	s_movk_i32 s0, 0x110
	v_and_b32_e32 v21, 15, v62
	v_lshl_add_u32 v66, v20, 2, 0
	v_mul_lo_u32 v20, v63, s0
	v_lshlrev_b32_e32 v22, 2, v24
	v_add_u32_e32 v20, 0, v20
	v_add_u32_e32 v23, 0, v36
	v_mul_u32_u24_e32 v21, 0x110, v21
	s_mov_b32 s53, 0
	v_lshl_add_u32 v64, v62, 2, 0
	s_waitcnt lgkmcnt(0)
	v_lshl_add_u64 v[42:43], s[54:55], 0, v[36:37]
	s_lshl_b32 s0, s3, 4
	v_mov_b32_e32 v67, 0x358637bd
	s_mov_b32 s1, 0x800000
	s_mov_b64 s[54:55], 0xae00800
	s_mov_b32 s2, 0xae00000
	v_add_u32_e32 v68, v20, v38
	v_add_u32_e32 v69, v23, v21
	v_lshlrev_b32_e32 v36, 1, v22
	s_mov_b32 s4, s33
	v_readfirstlane_b32 s98, v254
	s_nop 3
	s_bitcmp1_b32 s98, 8
	s_cbranch_scc0 .Lsprio0_skip
	s_setprio 1
.Lsprio0_skip:
	s_branch .LBB0_826
.LBB0_824:
	s_or_b64 exec, exec, s[60:61]

; __device__ __forceinline__ unsigned xb_add(unsigned* p, unsigned v) { return __hip_atomic_fetch_add(p, v, __ATOMIC_RELAXED, __HIP_MEMORY_SCOPE_AGENT); }
; __device__ __forceinline__ void xcd_barrier(const XcdBarrier& b) {
;     asm volatile("s_waitcnt vmcnt(0)" ::: "memory");
;     __syncthreads();
;     if (threadIdx.x == 0) {
;         unsigned* bar = b.bar;
;         __builtin_amdgcn_s_waitcnt(0);
;         const unsigned nloc = b.nloc, nx = b.nx;
;         const unsigned old = xb_add(&bar[XB_XSUB(b.x)], 1u);
.LBB0_833:
	s_setprio 0
	s_waitcnt vmcnt(0)
	s_barrier
	s_and_saveexec_b64 s[8:9], s[96:97]
	s_cbranch_execz .LBB0_870
	s_mov_b64 s[12:13], exec
	s_lshl_b32 s0, s83, 8
	v_mbcnt_lo_u32_b32 v0, s12, 0
	s_add_u32 s10, s94, s0
	v_mbcnt_hi_u32_b32 v0, s13, v0
	s_addc_u32 s11, s95, 0
	v_cmp_eq_u32_e32 vcc, 0, v0
	s_waitcnt vmcnt(0) expcnt(0) lgkmcnt(0)
	s_and_saveexec_b64 s[48:49], vcc
	s_cbranch_execz .LBB0_836
	s_bcnt1_i32_b64 s0, s[12:13]
	v_mov_b32_e32 v1, 0x1000
	v_mov_b32_e32 v2, s0
	global_atomic_add v1, v1, v2, s[10:11] offset:1024 sc0

; #define LAS __attribute__((address_space(3)))
; __device__ __forceinline__ void sgu_phase(const Params& p, LAS unsigned char* lds, int li, int tid, int G, bf16_t* dst) {
;     asm volatile("" : "+v"(tid));
;     unsigned char* ws = p.ws;
;     const int w = tid >> 6, l = tid & 63, lq = l & 15, g4 = l >> 4;
;     const bf16_t* ZVT = (const bf16_t*)(ws + OFF_ZVT2); bf16_t* Z0 = (bf16_t*)(ws + OFF_Z0);
;     const float* vss = (const float*)(ws + OFF_VSS);
;     LAS float* RI = (LAS float*)(lds + 34816);
;     const int c = tid >> 2, q0 = (tid & 3) * 32;
;     u32x4 raw[4]; f32x4 vs = {1.f, 1.f, 1.f, 1.f};
;     int item = blockIdx.x;
;     if (item < 2048) {
;         const int tb = item >> 3, g = item & 7, t0 = tb * 128;
; #pragma unroll
;         for (int i = 0; i < 4; ++i) raw[i] = *(const u32x4*)(ZVT + (size_t)(g * 128 + c) * T + t0 + q0 + 8 * i);
;         if (tid < 128) vs = *(const f32x4*)(vss + (size_t)(t0 + tid) * 32 + g * 4);
;     }
;     for (; item < 2048; item += G) {
;         const int tb = item >> 3, g = item & 7, t0 = tb * 128;
;         __syncthreads();
;         if (tid < 128) RI[tid] = rsqrtf(((vs[0] + vs[1]) + (vs[2] + vs[3])) * (1.f / 128.f) + EPS);
;         const size_t tok = (size_t)(t0 + 16 * w + lq);
;         const bf16_t* WS = (const bf16_t*)(ws + OFF_WSB) + (size_t)(li * 8 + g) * 128 * 128;
.LBB0_1561:
	s_or_b64 exec, exec, s[28:29]
	v_bfi_b32 v65, -16, v63, v62
	v_lshlrev_b32_e32 v22, 7, v65
	v_bfe_u32 v24, v62, 4, 2
	v_ashrrev_i32_e32 v23, 31, v22
	v_lshl_add_u64 v[22:23], v[22:23], 1, s[10:11]
	v_lshlrev_b32_e32 v36, 4, v24
	v_lshl_add_u64 v[22:23], v[22:23], 0, v[36:37]
	s_mov_b64 s[0:1], 0x90000
	v_lshl_add_u64 v[40:41], v[22:23], 0, s[0:1]
	s_movk_i32 s0, 0x110
	v_and_b32_e32 v21, 15, v62
	v_lshl_add_u32 v66, v20, 2, 0
	v_mul_lo_u32 v20, v63, s0
	v_lshlrev_b32_e32 v22, 2, v24
	v_add_u32_e32 v23, 0, v20
	v_add_u32_e32 v24, 0, v36
	v_mul_u32_u24_e32 v25, 0x110, v21
	s_waitcnt lgkmcnt(0)
	v_lshl_add_u64 v[20:21], s[26:27], 0, v[36:37]
	s_mov_b64 s[0:1], 0x1000
	s_mov_b32 s25, 0
	v_lshl_add_u32 v64, v62, 2, 0
	v_lshl_add_u64 v[42:43], v[20:21], 0, s[0:1]
	s_lshl_b32 s0, s3, 4
	v_mov_b32_e32 v67, 0x358637bd
	s_mov_b32 s1, 0x800000
	s_mov_b64 s[26:27], 0xae00800
	s_mov_b32 s2, 0xae00000
	v_add_u32_e32 v68, v23, v38
	v_add_u32_e32 v69, v24, v25
	v_lshlrev_b32_e32 v36, 1, v22
	s_mov_b32 s4, s33
	v_readfirstlane_b32 s98, v254
	s_nop 3
	s_bitcmp1_b32 s98, 8
	s_cbranch_scc0 .Lsprio1_skip
	s_setprio 1
.Lsprio1_skip:
	s_branch .LBB0_1564
.LBB0_1562:
	s_or_b64 exec, exec, s[36:37]

; __device__ __forceinline__ unsigned xb_add(unsigned* p, unsigned v) { return __hip_atomic_fetch_add(p, v, __ATOMIC_RELAXED, __HIP_MEMORY_SCOPE_AGENT); }
; __device__ __forceinline__ void xcd_barrier(const XcdBarrier& b) {
;     asm volatile("s_waitcnt vmcnt(0)" ::: "memory");
;     __syncthreads();
;     if (threadIdx.x == 0) {
;         unsigned* bar = b.bar;
;         __builtin_amdgcn_s_waitcnt(0);
;         const unsigned nloc = b.nloc, nx = b.nx;
;         const unsigned old = xb_add(&bar[XB_XSUB(b.x)], 1u);
.LBB0_1571:
	s_setprio 0
	s_waitcnt vmcnt(0)
	s_barrier
	s_and_saveexec_b64 s[6:7], s[96:97]
	s_cbranch_execz .LBB0_1608
	s_mov_b64 s[14:15], exec
	s_lshl_b32 s0, s84, 8
	v_mbcnt_lo_u32_b32 v0, s14, 0
	s_add_u32 s10, s88, s0
	v_mbcnt_hi_u32_b32 v0, s15, v0
	s_addc_u32 s11, s89, 0
	v_cmp_eq_u32_e32 vcc, 0, v0
	s_waitcnt vmcnt(0) expcnt(0) lgkmcnt(0)
	s_and_saveexec_b64 s[18:19], vcc
	s_cbranch_execz .LBB0_1574
	s_bcnt1_i32_b64 s0, s[14:15]
	v_mov_b32_e32 v1, 0x1000
	v_mov_b32_e32 v2, s0
	global_atomic_add v1, v1, v2, s[10:11] offset:1024 sc0
